# dense gate pass: the two per-lane constant loads (dt_bias, a_log) hoisted out of the two-token loop
# baseline (speedup 1.0000x reference)
.LBB0_240:
	s_or_b64 exec, exec, s[10:11]
	v_readlane_b32 s20, v42, 1
	v_readlane_b32 s21, v43, 1
	v_readlane_b32 s22, v44, 1
	v_readlane_b32 s23, v45, 1
	v_lshl_add_u32 v2, s2, 9, v164
	v_and_b32_e32 v3, 3, v2
	v_bfe_u32 v34, v2, 2, 2
	v_lshrrev_b32_e32 v50, 4, v2
	v_lshl_add_u32 v36, v3, 2, v34
	v_cmp_ne_u32_e64 s[6:7], 0, v3
	v_cmp_gt_u32_e64 s[14:15], 3, v3
	v_add_u32_e32 v4, -4, v36
	v_mov_b32_e32 v5, 0
	v_lshlrev_b64 v[4:5], 2, v[4:5]
	v_lshl_add_u64 v[42:43], s[20:21], 0, v[4:5]
	v_lshl_add_u64 v[44:45], s[22:23], 0, v[4:5]
	v_lshlrev_b32_e32 v4, 4, v34
	v_lshl_add_u32 v4, v3, 2, v4
	v_mov_b32_e32 v5, 0
	s_add_u32 s18, s28, 0xfd00000
	s_addc_u32 s19, s29, 0
	v_lshl_add_u64 v[40:41], s[18:19], 0, v[4:5]
	v_mov_b32_e32 v53, 0
	v_mov_b32_e32 v71, 0
	v_mov_b32_e32 v38, 0
	s_mov_b32 s12, 0
	s_mov_b64 s[8:9], exec
	s_and_b64 exec, exec, s[14:15]
	s_and_saveexec_b64 s[16:17], s[6:7]
	global_load_dword v54, v[42:43], off
	global_load_dword v55, v[44:45], off
	s_waitcnt vmcnt(0)
	s_or_b64 exec, exec, s[16:17]
.Lgp_loop:
	v_mov_b32_e32 v52, v50
	v_mul_u32_u24_e32 v70, 0x1200, v50
	v_lshl_add_u64 v[2:3], s[0:1], 0, v[70:71]
	s_and_saveexec_b64 s[16:17], s[6:7]
	s_xor_b64 s[16:17], exec, s[16:17]
	s_cbranch_execz .Lgp_238
	v_lshlrev_b32_e32 v4, 1, v36
	v_mov_b32_e32 v5, v38
	v_lshl_add_u64 v[2:3], v[2:3], 0, v[4:5]
	global_load_ushort v2, v[2:3], off offset:4088
	s_nop 0
	v_mov_b32_e32 v3, v54
	s_waitcnt vmcnt(0)
	v_lshlrev_b32_e32 v2, 16, v2
	s_waitcnt vmcnt(0)
	v_add_f32_e32 v2, v3, v2
	v_cmp_nlt_f32_e32 vcc, s50, v2
	s_and_saveexec_b64 s[18:19], vcc
	s_cbranch_execz .Lgp_237
	v_mul_f32_e32 v3, 0x3fb8aa3b, v2
	v_rndne_f32_e32 v4, v3
	v_sub_f32_e32 v5, v3, v4
	v_fma_f32 v3, v2, s51, -v3
	v_fmac_f32_e32 v3, 0x32a5705f, v2
	v_add_f32_e32 v3, v5, v3
	v_cvt_i32_f32_e32 v4, v4
	v_exp_f32_e32 v3, v3
	v_cmp_ngt_f32_e32 vcc, s52, v2
	v_ldexp_f32 v3, v3, v4
	s_nop 0
	v_cndmask_b32_e32 v3, 0, v3, vcc
	v_cmp_nlt_f32_e32 vcc, s53, v2
	s_nop 1
	v_cndmask_b32_e32 v16, v47, v3, vcc
	v_add_f32_e32 v4, 1.0, v16
	v_add_f32_e32 v2, -1.0, v4
	v_sub_f32_e32 v3, v2, v4
	v_add_f32_e32 v3, 1.0, v3
	v_sub_f32_e32 v2, v16, v2
	v_add_f32_e32 v5, v2, v3
	v_frexp_mant_f32_e32 v6, v4
	v_cvt_f64_f32_e32 v[2:3], v4
	v_frexp_exp_i32_f64_e32 v2, v[2:3]
	v_cmp_gt_f32_e32 vcc, s55, v6
	s_nop 1
	v_subbrev_co_u32_e32 v10, vcc, 0, v2, vcc
	v_sub_u32_e32 v2, 0, v10
	v_ldexp_f32 v3, v4, v2
	v_add_f32_e32 v4, -1.0, v3
	v_add_f32_e32 v6, 1.0, v3
	v_ldexp_f32 v2, v5, v2
	v_add_f32_e32 v5, 1.0, v4
	v_add_f32_e32 v7, -1.0, v6
	v_sub_f32_e32 v5, v3, v5
	v_sub_f32_e32 v3, v3, v7
	v_add_f32_e32 v5, v2, v5
	v_add_f32_e32 v2, v2, v3
	v_add_f32_e32 v11, v6, v2
	v_rcp_f32_e32 v13, v11
	v_sub_f32_e32 v3, v6, v11
	v_add_f32_e32 v12, v2, v3
	v_add_f32_e32 v3, v4, v5
	v_mul_f32_e32 v15, v3, v13
	v_sub_f32_e32 v2, v4, v3
	v_mul_f32_e32 v4, v11, v15
	v_fma_f32 v6, v15, v11, -v4
	v_fmac_f32_e32 v6, v15, v12
	v_add_f32_e32 v14, v5, v2
	v_add_f32_e32 v2, v4, v6
	v_sub_f32_e32 v5, v3, v2
	v_pk_add_f32 v[8:9], v[2:3], v[4:5] neg_lo:[0,1] neg_hi:[0,1]
	v_mov_b32_e32 v7, v2
	v_pk_add_f32 v[2:3], v[8:9], v[6:7] neg_lo:[0,1] neg_hi:[0,1]
	v_cmp_neq_f32_e32 vcc, s54, v16
	v_add_f32_e32 v3, v14, v3
	v_add_f32_e32 v2, v2, v3
	v_add_f32_e32 v3, v5, v2
	v_mul_f32_e32 v14, v13, v3
	v_mul_f32_e32 v4, v11, v14
	v_fma_f32 v6, v14, v11, -v4
	v_fmac_f32_e32 v6, v14, v12
	v_sub_f32_e32 v5, v5, v3
	v_add_f32_e32 v11, v2, v5
	v_add_f32_e32 v2, v4, v6
	v_sub_f32_e32 v5, v3, v2
	v_pk_add_f32 v[8:9], v[2:3], v[4:5] neg_lo:[0,1] neg_hi:[0,1]
	v_mov_b32_e32 v7, v2
	v_pk_add_f32 v[2:3], v[8:9], v[6:7] neg_lo:[0,1] neg_hi:[0,1]
	s_nop 0
	v_add_f32_e32 v3, v11, v3
	v_add_f32_e32 v2, v2, v3
	v_add_f32_e32 v3, v15, v14
	v_add_f32_e32 v2, v5, v2
	v_sub_f32_e32 v4, v3, v15
	v_mul_f32_e32 v2, v13, v2
	v_sub_f32_e32 v4, v14, v4
	v_add_f32_e32 v4, v4, v2
	v_add_f32_e32 v6, v3, v4
	v_mul_f32_e32 v7, v6, v6
	v_fmamk_f32 v2, v7, 0x3e9b6dac, v35
	v_fmaak_f32 v49, v7, v2, 0x3f2aaada
	v_cvt_f32_i32_e32 v2, v10
	v_sub_f32_e32 v3, v6, v3
	v_sub_f32_e32 v3, v4, v3
	v_ldexp_f32 v8, v3, 1
	v_mul_f32_e32 v3, v6, v7
	v_ldexp_f32 v5, v6, 1
	v_pk_mul_f32 v[6:7], v[2:3], v[48:49]
	s_nop 0
	v_fma_f32 v4, v2, s56, -v6
	v_fmac_f32_e32 v4, 0xb102e308, v2
	v_pk_add_f32 v[2:3], v[6:7], v[4:5]
	s_nop 0
	v_sub_f32_e32 v5, v3, v5
	v_sub_f32_e32 v5, v7, v5
	v_add_f32_e32 v9, v8, v5
	v_mov_b32_e32 v8, v6
	v_pk_add_f32 v[6:7], v[2:3], v[6:7] neg_lo:[0,1] neg_hi:[0,1]
	v_pk_add_f32 v[10:11], v[2:3], v[8:9]
	v_mov_b32_e32 v5, v2
	v_mov_b32_e32 v7, v11
	v_pk_add_f32 v[12:13], v[4:5], v[6:7] neg_lo:[0,1] neg_hi:[0,1]
	v_pk_add_f32 v[4:5], v[4:5], v[6:7]
	v_mov_b32_e32 v8, v9
	v_pk_add_f32 v[6:7], v[4:5], v[2:3] op_sel:[1,0] op_sel_hi:[0,1] neg_lo:[0,1] neg_hi:[0,1]
	v_pk_add_f32 v[14:15], v[10:11], v[6:7] op_sel_hi:[1,0] neg_lo:[0,1] neg_hi:[0,1]
	v_mov_b32_e32 v10, v11
	v_mov_b32_e32 v11, v5
	v_pk_mov_b32 v[6:7], v[2:3], v[6:7] op_sel:[1,0]
	v_mov_b32_e32 v9, v2
	v_pk_add_f32 v[6:7], v[10:11], v[6:7] neg_lo:[0,1] neg_hi:[0,1]
	v_mov_b32_e32 v14, v12
	v_pk_add_f32 v[2:3], v[8:9], v[6:7] neg_lo:[0,1] neg_hi:[0,1]
	v_mov_b32_e32 v13, v5
	v_pk_add_f32 v[6:7], v[14:15], v[2:3]
	s_nop 0
	v_pk_add_f32 v[8:9], v[6:7], v[6:7] op_sel:[0,1] op_sel_hi:[1,0]
	s_nop 0
	v_pk_add_f32 v[4:5], v[4:5], v[8:9] op_sel:[1,0] op_sel_hi:[0,1]
	v_mov_b32_e32 v7, v4
	v_pk_add_f32 v[10:11], v[6:7], v[12:13] neg_lo:[0,1] neg_hi:[0,1]
	v_mov_b32_e32 v3, v8
	v_sub_f32_e32 v5, v6, v10
	v_pk_add_f32 v[2:3], v[2:3], v[10:11] neg_lo:[0,1] neg_hi:[0,1]
	v_sub_f32_e32 v5, v12, v5
	v_add_f32_e32 v2, v2, v5
	v_add_f32_e32 v2, v2, v3
	v_add_f32_e32 v2, v4, v2
	v_cndmask_b32_e32 v2, v47, v2, vcc
	v_cmp_lt_f32_e64 vcc, |v16|, s57
	s_nop 1
	v_cndmask_b32_e32 v2, v2, v16, vcc
.Lgp_237:
	s_or_b64 exec, exec, s[18:19]
	v_mov_b32_e32 v3, v55
	s_waitcnt vmcnt(0)
	v_mul_f32_e32 v4, 0x3fb8aa3b, v3
	v_rndne_f32_e32 v5, v4
	v_fma_f32 v6, v3, s51, -v4
	v_sub_f32_e32 v4, v4, v5
	v_fmac_f32_e32 v6, 0x32a5705f, v3
	v_add_f32_e32 v4, v4, v6
	v_cvt_i32_f32_e32 v5, v5
	v_exp_f32_e32 v4, v4
	v_cmp_ngt_f32_e32 vcc, s52, v3
	v_ldexp_f32 v4, v4, v5
	s_nop 0
	v_cndmask_b32_e32 v4, 0, v4, vcc
	v_cmp_nlt_f32_e32 vcc, s53, v3
	s_nop 1
	v_cndmask_b32_e32 v3, v47, v4, vcc
	v_mul_f32_e64 v2, v2, -v3
	v_mul_f32_e32 v3, 0x3fb8aa3b, v2
	v_fma_f32 v4, v2, s51, -v3
	v_rndne_f32_e32 v5, v3
	v_fmac_f32_e32 v4, 0x32a5705f, v2
	v_sub_f32_e32 v3, v3, v5
	v_add_f32_e32 v3, v3, v4
	v_cvt_i32_f32_e32 v5, v5
	v_exp_f32_e32 v3, v3
	v_cmp_ngt_f32_e32 vcc, s52, v2
	v_ldexp_f32 v3, v3, v5
	s_nop 0
	v_cndmask_b32_e32 v3, 0, v3, vcc
	v_cmp_nlt_f32_e32 vcc, s53, v2
	s_nop 1
	v_cndmask_b32_e32 v4, v47, v3, vcc
